# conv: chunk-start wait+barrier moved to the loop back-edge so the first chunk's ring fill loads issue behind the parameter loads without waiting
# baseline (speedup 1.0000x reference)
.LBB0_451:
	s_add_i32 s71, s71, s64
	s_add_i32 s38, s38, s39
	s_add_i32 s54, s54, s39
	s_cmpk_gt_i32 s71, 0xff
	s_cbranch_scc1 .LBB0_468
	s_waitcnt vmcnt(0)
	s_barrier
.LBB0_452:
	s_lshl_b32 s20, s71, 7
	s_and_b32 s16, s20, 0x780
	s_sub_i32 s21, 29, s16
	s_mov_b64 s[16:17], 0
	v_mov_b32_e32 v112, v204
	v_mov_b32_e32 v113, v189
	v_mov_b32_e32 v114, v203
	v_add_u32_e32 v122, s38, v113
	v_ashrrev_i32_e32 v123, 31, v122
	v_lshlrev_b64 v[120:121], 11, v[122:123]
	v_lshl_add_u64 v[120:121], v[110:111], 0, v[120:121]
	s_mov_b32 s18, 0x2000
	s_mov_b32 s19, 0
	v_mov_b64_e32 v[0:1], 0
	v_mov_b64_e32 v[2:3], 0
	v_mov_b64_e32 v[4:5], 0
	v_mov_b64_e32 v[6:7], 0
	v_mov_b64_e32 v[8:9], 0
	v_mov_b64_e32 v[10:11], 0
	v_mov_b64_e32 v[12:13], 0
	v_mov_b64_e32 v[14:15], 0
	v_mov_b64_e32 v[16:17], 0
	v_mov_b64_e32 v[18:19], 0
	v_mov_b64_e32 v[20:21], 0
	v_mov_b64_e32 v[22:23], 0
	v_mov_b64_e32 v[24:25], 0
	v_mov_b64_e32 v[26:27], 0
	v_mov_b64_e32 v[28:29], 0
	v_mov_b64_e32 v[30:31], 0
	v_mov_b64_e32 v[156:157], 0
	v_mov_b64_e32 v[158:159], 0
	v_mov_b64_e32 v[160:161], 0
	v_mov_b64_e32 v[162:163], 0
	v_mov_b64_e32 v[164:165], 0
	v_mov_b64_e32 v[166:167], 0
	v_mov_b64_e32 v[168:169], 0
	v_mov_b64_e32 v[170:171], 0
	v_mov_b64_e32 v[172:173], 0
	v_mov_b64_e32 v[174:175], 0
	v_mov_b64_e32 v[176:177], 0
	v_mov_b64_e32 v[178:179], 0
	v_mov_b64_e32 v[180:181], 0
	v_mov_b64_e32 v[182:183], 0
	v_mov_b64_e32 v[116:117], 0
	v_mov_b64_e32 v[118:119], 0
	v_cmp_lt_i32_e32 vcc, s21, v113
	s_and_saveexec_b64 s[16:17], vcc
	global_load_dwordx4 v[0:3], v[120:121], off nt
	s_mov_b64 exec, s[16:17]
	v_add_u32_e32 v113, 4, v113
	v_lshl_add_u64 v[120:121], v[120:121], 0, s[18:19]
	v_cmp_lt_i32_e32 vcc, s21, v113
	s_and_saveexec_b64 s[16:17], vcc
	global_load_dwordx4 v[4:7], v[120:121], off nt
	s_mov_b64 exec, s[16:17]
	v_add_u32_e32 v113, 4, v113
	v_lshl_add_u64 v[120:121], v[120:121], 0, s[18:19]
	v_cmp_lt_i32_e32 vcc, s21, v113
	s_and_saveexec_b64 s[16:17], vcc
	global_load_dwordx4 v[8:11], v[120:121], off nt
	s_mov_b64 exec, s[16:17]
	v_add_u32_e32 v113, 4, v113
	v_lshl_add_u64 v[120:121], v[120:121], 0, s[18:19]
	v_cmp_lt_i32_e32 vcc, s21, v113
	s_and_saveexec_b64 s[16:17], vcc
	global_load_dwordx4 v[12:15], v[120:121], off nt
	s_mov_b64 exec, s[16:17]
	v_add_u32_e32 v113, 4, v113
	v_lshl_add_u64 v[120:121], v[120:121], 0, s[18:19]
	v_cmp_lt_i32_e32 vcc, s21, v113
	s_and_saveexec_b64 s[16:17], vcc
	global_load_dwordx4 v[16:19], v[120:121], off nt
	s_mov_b64 exec, s[16:17]
	v_add_u32_e32 v113, 4, v113
	v_lshl_add_u64 v[120:121], v[120:121], 0, s[18:19]
	v_cmp_lt_i32_e32 vcc, s21, v113
	s_and_saveexec_b64 s[16:17], vcc
	global_load_dwordx4 v[20:23], v[120:121], off nt
	s_mov_b64 exec, s[16:17]
	v_add_u32_e32 v113, 4, v113
	v_lshl_add_u64 v[120:121], v[120:121], 0, s[18:19]
	v_cmp_lt_i32_e32 vcc, s21, v113
	s_and_saveexec_b64 s[16:17], vcc
	global_load_dwordx4 v[24:27], v[120:121], off nt
	s_mov_b64 exec, s[16:17]
	v_add_u32_e32 v113, 4, v113
	v_lshl_add_u64 v[120:121], v[120:121], 0, s[18:19]
	v_cmp_lt_i32_e32 vcc, s21, v113
	s_and_saveexec_b64 s[16:17], vcc
	global_load_dwordx4 v[28:31], v[120:121], off nt
	s_mov_b64 exec, s[16:17]
	v_add_u32_e32 v113, 4, v113
	v_lshl_add_u64 v[120:121], v[120:121], 0, s[18:19]
	v_cmp_lt_i32_e32 vcc, s21, v113
	s_and_saveexec_b64 s[16:17], vcc
	global_load_dwordx4 v[156:159], v[120:121], off nt
	s_mov_b64 exec, s[16:17]
	v_add_u32_e32 v113, 4, v113
	v_lshl_add_u64 v[120:121], v[120:121], 0, s[18:19]
	v_cmp_lt_i32_e32 vcc, s21, v113
	s_and_saveexec_b64 s[16:17], vcc
	global_load_dwordx4 v[160:163], v[120:121], off nt
	s_mov_b64 exec, s[16:17]
	v_add_u32_e32 v113, 4, v113
	v_lshl_add_u64 v[120:121], v[120:121], 0, s[18:19]
	v_cmp_lt_i32_e32 vcc, s21, v113
	s_and_saveexec_b64 s[16:17], vcc
	global_load_dwordx4 v[164:167], v[120:121], off nt
	s_mov_b64 exec, s[16:17]
	v_add_u32_e32 v113, 4, v113
	v_lshl_add_u64 v[120:121], v[120:121], 0, s[18:19]
	v_cmp_lt_i32_e32 vcc, s21, v113
	s_and_saveexec_b64 s[16:17], vcc
	global_load_dwordx4 v[168:171], v[120:121], off nt
	s_mov_b64 exec, s[16:17]
	v_add_u32_e32 v113, 4, v113
	v_lshl_add_u64 v[120:121], v[120:121], 0, s[18:19]
	v_cmp_lt_i32_e32 vcc, s21, v113
	s_and_saveexec_b64 s[16:17], vcc
	global_load_dwordx4 v[172:175], v[120:121], off nt
	s_mov_b64 exec, s[16:17]
	v_add_u32_e32 v113, 4, v113
	v_lshl_add_u64 v[120:121], v[120:121], 0, s[18:19]
	v_cmp_lt_i32_e32 vcc, s21, v113
	s_and_saveexec_b64 s[16:17], vcc
	global_load_dwordx4 v[176:179], v[120:121], off nt
	s_mov_b64 exec, s[16:17]
	v_add_u32_e32 v113, 4, v113
	v_lshl_add_u64 v[120:121], v[120:121], 0, s[18:19]
	v_cmp_lt_i32_e32 vcc, s21, v113
	s_and_saveexec_b64 s[16:17], vcc
	global_load_dwordx4 v[180:183], v[120:121], off nt
	s_mov_b64 exec, s[16:17]
	v_add_u32_e32 v113, 4, v113
	v_lshl_add_u64 v[120:121], v[120:121], 0, s[18:19]
	v_cmp_gt_u32_e32 vcc, 0x100, v207
	s_and_saveexec_b64 s[16:17], vcc
	v_cmp_lt_i32_e32 vcc, s21, v113
	s_and_b64 exec, exec, vcc
	global_load_dwordx4 v[116:119], v[120:121], off nt
	s_mov_b64 exec, s[16:17]
	v_add_u32_e32 v123, 0x10000, v112
	s_waitcnt vmcnt(0)
	ds_write_b128 v112, v[0:3]
	ds_write_b128 v112, v[4:7] offset:8192
	ds_write_b128 v112, v[8:11] offset:16384
	ds_write_b128 v112, v[12:15] offset:24576
	ds_write_b128 v112, v[16:19] offset:32768
	ds_write_b128 v112, v[20:23] offset:40960
	ds_write_b128 v112, v[24:27] offset:49152
	ds_write_b128 v112, v[28:31] offset:57344
	ds_write_b128 v123, v[156:159]
	ds_write_b128 v123, v[160:163] offset:8192
	ds_write_b128 v123, v[164:167] offset:16384
	ds_write_b128 v123, v[168:171] offset:24576
	ds_write_b128 v123, v[172:175] offset:32768
	ds_write_b128 v123, v[176:179] offset:40960
	ds_write_b128 v123, v[180:183] offset:49152
	v_cmp_gt_u32_e32 vcc, 0x100, v207
	s_and_saveexec_b64 s[16:17], vcc
	ds_write_b128 v123, v[116:119] offset:57344
	s_mov_b64 exec, s[16:17]
